# one static priority raise (s_setprio 1) for waves 4-7 during the attention item loop, reset at loop exit
# baseline (speedup 1.0000x reference)
.LBB0_478:
	s_or_b64 exec, exec, s[6:7]
	v_and_b32_e32 v94, 0xff, v51
	s_lshl_b32 s2, s9, 1
	v_ashrrev_i32_e32 v53, 5, v51
	v_and_b32_e32 v80, -8, v53
	v_ashrrev_i32_e32 v55, 5, v52
	v_and_b32_e32 v82, -8, v55
	v_ashrrev_i32_e32 v56, 5, v0
	v_and_b32_e32 v84, -8, v56
	v_ashrrev_i32_e32 v57, 5, v54
	v_and_b32_e32 v86, -8, v57
	v_ashrrev_i32_e32 v87, 31, v86
	v_and_b32_e32 v35, 15, v51
	v_ashrrev_i32_e32 v50, 2, v51
	v_or_b32_e32 v0, s8, v35
	v_and_b32_e32 v34, -16, v50
	v_add_u32_e32 v38, v0, v34
	v_ashrrev_i32_e32 v39, 31, v38
	v_lshlrev_b64 v[38:39], s5, v[38:39]
	s_mov_b32 s5, s3
	v_lshl_add_u64 v[38:39], v[38:39], 0, s[4:5]
	v_readlane_b32 s4, v254, 1
	v_readlane_b32 s5, v254, 2
	s_movk_i32 s6, 0x1400
	v_bfe_u32 v58, v51, 4, 2
	v_mov_b64_e32 v[40:41], s[4:5]
	v_mad_u64_u32 v[40:41], s[4:5], v38, s6, v[40:41]
	v_ashrrev_i32_e32 v37, 6, v51
	v_cmp_eq_u32_e64 s[4:5], 0, v58
	v_mad_i32_i24 v41, v39, s6, v41
	v_lshrrev_b32_e32 v0, 1, v51
	v_bfi_b32 v95, -16, v50, v51
	v_lshlrev_b32_e32 v59, 4, v37
	v_writelane_b32 v254, s4, 24
	v_lshrrev_b32_e32 v51, 6, v51
	v_lshrrev_b32_e32 v52, 6, v52
	v_lshl_add_u64 v[38:39], v[40:41], 0, s[2:3]
	v_or_b32_e32 v96, v59, v35
	v_writelane_b32 v254, s5, 25
	s_movk_i32 s2, 0x90
	v_and_b32_e32 v62, 12, v51
	s_mov_b32 s4, 0xfffffe0
	v_and_b32_e32 v52, 12, v52
	v_and_b32_e32 v34, 24, v0
	v_and_or_b32 v51, v53, s4, v62
	v_and_or_b32 v52, v55, s4, v52
	v_and_or_b32 v53, v56, s4, v62
	v_lshrrev_b32_e32 v54, 6, v54
	v_mul_lo_u32 v55, v96, s2
	v_lshlrev_b32_e32 v56, 4, v58
	v_lshlrev_b32_e32 v0, 1, v34
	v_and_b32_e32 v54, 12, v54
	v_add3_u32 v97, 0, v55, v56
	v_add_u32_e32 v55, 1, v37
	v_lshl_add_u64 v[38:39], v[38:39], 0, v[0:1]
	v_and_or_b32 v54, v57, s4, v54
	v_lshlrev_b32_e32 v57, 4, v55
	global_load_dwordx4 v[42:45], v[38:39], off offset:576
	global_load_dwordx4 v[46:49], v[38:39], off offset:512
	v_lshl_add_u32 v38, v36, 1, 0
	v_lshlrev_b32_e32 v36, 3, v58
	v_lshlrev_b32_e32 v60, 2, v58
	v_or_b32_e32 v58, v57, v35
	v_mul_lo_u32 v58, v58, s2
	v_add3_u32 v98, 0, v58, v56
	v_add_u32_e32 v58, 2, v37
	v_lshlrev_b32_e32 v62, 4, v58
	v_or_b32_e32 v63, v62, v35
	v_mul_lo_u32 v63, v63, s2
	v_add3_u32 v99, 0, v63, v56
	v_add_u32_e32 v63, 3, v37
	v_lshlrev_b32_e32 v64, 4, v63
	v_or_b32_e32 v65, v64, v35
	v_mul_lo_u32 v65, v65, s2
	v_add3_u32 v100, 0, v65, v56
	v_add_u32_e32 v65, 4, v37
	v_lshlrev_b32_e32 v66, 4, v65
	v_or_b32_e32 v67, v66, v35
	v_mul_lo_u32 v67, v67, s2
	v_add3_u32 v101, 0, v67, v56
	v_add_u32_e32 v67, 5, v37
	v_lshlrev_b32_e32 v68, 4, v67
	v_or_b32_e32 v69, v68, v35
	v_mul_lo_u32 v69, v69, s2
	v_add3_u32 v102, 0, v69, v56
	v_add_u32_e32 v69, 6, v37
	v_lshlrev_b32_e32 v70, 4, v69
	v_or_b32_e32 v71, v70, v35
	v_mul_lo_u32 v71, v71, s2
	v_add3_u32 v103, 0, v71, v56
	v_add_u32_e32 v71, 7, v37
	v_lshlrev_b32_e32 v72, 4, v71
	v_or_b32_e32 v73, v72, v35
	v_mul_lo_u32 v73, v73, s2
	v_add3_u32 v104, 0, v73, v56
	v_add_u32_e32 v73, 8, v37
	v_lshlrev_b32_e32 v74, 4, v73
	v_or_b32_e32 v75, v74, v35
	v_mul_lo_u32 v75, v75, s2
	v_add_u32_e32 v61, 0x80, v96
	v_add3_u32 v105, 0, v75, v56
	v_or_b32_e32 v56, v60, v59
	v_mul_lo_u32 v39, v90, s2
	v_mul_lo_u32 v40, v91, s2
	v_mul_lo_u32 v41, v92, s2
	v_mul_lo_u32 v50, v93, s2
	v_sub_u32_e32 v59, v61, v56
	s_movk_i32 s18, 0x81
	s_movk_i32 s2, 0x100
	v_cmp_gt_u32_e32 vcc, s18, v59
	v_cmp_gt_i32_e64 s[4:5], s2, v56
	s_and_b64 s[4:5], s[4:5], vcc
	s_movk_i32 s28, 0x7f
	v_writelane_b32 v254, s4, 9
	v_or_b32_e32 v59, 1, v56
	v_sub_u32_e32 v75, v61, v59
	v_writelane_b32 v254, s5, 10
	v_cmp_lt_i32_e64 s[4:5], s28, v56
	v_cmp_gt_u32_e32 vcc, s18, v75
	s_movk_i32 s16, 0x7e
	v_writelane_b32 v253, s4, 59
	s_movk_i32 s29, 0x230
	v_mad_u32_u24 v35, v35, s29, 0
	v_writelane_b32 v253, s5, 60
	v_cmp_gt_i32_e64 s[4:5], s2, v59
	s_and_b64 s[4:5], s[4:5], vcc
	v_or_b32_e32 v59, 2, v56
	v_writelane_b32 v254, s4, 20
	v_sub_u32_e32 v75, v61, v59
	v_cmp_gt_u32_e32 vcc, s18, v75
	v_writelane_b32 v254, s5, 21
	v_cmp_lt_i32_e64 s[4:5], s16, v56
	v_or_b32_e32 v56, 3, v56
	v_lshlrev_b32_e32 v37, 5, v37
	v_writelane_b32 v254, s4, 22
	v_lshlrev_b32_e32 v55, 5, v55
	v_add3_u32 v107, v35, v37, v36
	v_writelane_b32 v254, s5, 23
	v_cmp_gt_i32_e64 s[4:5], s2, v59
	s_and_b64 s[4:5], s[4:5], vcc
	v_add3_u32 v106, v35, v55, v36
	v_writelane_b32 v254, s4, 26
	v_lshl_add_u32 v0, v94, 1, 0
	v_mul_lo_u32 v51, v51, s29
	v_writelane_b32 v254, s5, 27
	v_cmp_lt_i32_e64 s[4:5], s28, v59
	v_sub_u32_e32 v59, v61, v56
	v_cmp_gt_u32_e32 vcc, s18, v59
	v_writelane_b32 v254, s4, 28
	v_mul_lo_u32 v52, v52, s29
	v_mul_lo_u32 v53, v53, s29
	v_writelane_b32 v254, s5, 29
	v_cmp_gt_i32_e64 s[4:5], s2, v56
	s_and_b64 s[4:5], s[4:5], vcc
	v_mul_lo_u32 v54, v54, s29
	v_writelane_b32 v254, s4, 30
	v_add_u32_e32 v124, v38, v39
	v_add_u32_e32 v125, v38, v40
	v_writelane_b32 v254, s5, 31
	v_cmp_lt_i32_e64 s[4:5], s28, v56
	v_or_b32_e32 v56, v57, v60
	v_sub_u32_e32 v57, v61, v56
	v_writelane_b32 v254, s4, 32
	v_cmp_gt_u32_e32 vcc, s18, v57
	v_or_b32_e32 v57, 1, v56
	v_writelane_b32 v254, s5, 33
	v_cmp_gt_i32_e64 s[4:5], s2, v56
	s_and_b64 s[4:5], s[4:5], vcc
	v_sub_u32_e32 v59, v61, v57
	v_writelane_b32 v254, s4, 34
	v_cmp_gt_u32_e32 vcc, s18, v59
	v_add_u32_e32 v126, v38, v41
	v_writelane_b32 v254, s5, 35
	v_cmp_lt_i32_e64 s[4:5], s28, v56
	v_add_u32_e32 v127, v38, v50
	v_add_u32_e32 v128, v0, v51
	v_writelane_b32 v254, s4, 36
	v_add_u32_e32 v129, v0, v52
	v_add_u32_e32 v130, v0, v53
	v_writelane_b32 v254, s5, 37
	v_cmp_gt_i32_e64 s[4:5], s2, v57
	s_and_b64 s[4:5], s[4:5], vcc
	v_or_b32_e32 v57, 2, v56
	v_writelane_b32 v254, s4, 38
	v_sub_u32_e32 v59, v61, v57
	v_cmp_gt_u32_e32 vcc, s18, v59
	v_writelane_b32 v254, s5, 39
	v_cmp_lt_i32_e64 s[4:5], s16, v56
	v_or_b32_e32 v56, 3, v56
	v_add_u32_e32 v131, v0, v54
	v_writelane_b32 v254, s4, 40
	v_lshlrev_b32_e32 v0, 1, v34
	v_lshlrev_b32_e32 v88, 1, v36
	v_writelane_b32 v254, s5, 41
	v_cmp_gt_i32_e64 s[4:5], s2, v57
	s_and_b64 s[4:5], s[4:5], vcc
	s_waitcnt vmcnt(1)
	v_mov_b64_e32 v[38:39], v[42:43]
	v_writelane_b32 v254, s4, 42
	v_ashrrev_i32_e32 v81, 31, v80
	v_ashrrev_i32_e32 v83, 31, v82
	v_writelane_b32 v254, s5, 43
	v_cmp_lt_i32_e64 s[4:5], s28, v57
	v_sub_u32_e32 v57, v61, v56
	v_cmp_gt_u32_e32 vcc, s18, v57
	v_writelane_b32 v254, s4, 44
	v_ashrrev_i32_e32 v85, 31, v84
	v_mov_b64_e32 v[40:41], v[44:45]
	v_writelane_b32 v254, s5, 45
	v_cmp_gt_i32_e64 s[4:5], s2, v56
	s_and_b64 s[4:5], s[4:5], vcc
	s_nop 0
	v_writelane_b32 v254, s4, 46
	s_nop 1
	v_writelane_b32 v254, s5, 47
	v_cmp_lt_i32_e64 s[4:5], s28, v56
	v_or_b32_e32 v56, v62, v60
	v_sub_u32_e32 v57, v61, v56
	v_writelane_b32 v254, s4, 48
	v_cmp_gt_u32_e32 vcc, s18, v57
	v_or_b32_e32 v57, 1, v56
	v_writelane_b32 v254, s5, 49
	v_cmp_gt_i32_e64 s[4:5], s2, v56
	s_and_b64 s[4:5], s[4:5], vcc
	v_sub_u32_e32 v59, v61, v57
	v_writelane_b32 v254, s4, 50
	v_cmp_gt_u32_e32 vcc, s18, v59
	s_nop 0
	v_writelane_b32 v254, s5, 51
	v_cmp_lt_i32_e64 s[4:5], s28, v56
	s_nop 1
	v_writelane_b32 v254, s4, 52
	s_nop 1
	v_writelane_b32 v254, s5, 53
	v_cmp_gt_i32_e64 s[4:5], s2, v57
	s_and_b64 s[4:5], s[4:5], vcc
	v_or_b32_e32 v57, 2, v56
	v_writelane_b32 v254, s4, 54
	v_sub_u32_e32 v59, v61, v57
	v_cmp_gt_u32_e32 vcc, s18, v59
	v_writelane_b32 v254, s5, 55
	v_cmp_lt_i32_e64 s[4:5], s16, v56
	v_or_b32_e32 v56, 3, v56
	s_nop 0
	v_writelane_b32 v254, s4, 56
	s_nop 1
	v_writelane_b32 v254, s5, 57
	v_cmp_gt_i32_e64 s[4:5], s2, v57
	s_and_b64 s[4:5], s[4:5], vcc
	s_nop 0
	v_writelane_b32 v254, s4, 58
	s_nop 1
	v_writelane_b32 v254, s5, 59
	v_cmp_lt_i32_e64 s[4:5], s28, v57
	v_sub_u32_e32 v57, v61, v56
	v_cmp_gt_u32_e32 vcc, s18, v57
	v_writelane_b32 v254, s4, 60
	s_nop 1
	v_writelane_b32 v254, s5, 61
	v_cmp_gt_i32_e64 s[4:5], s2, v56
	s_and_b64 s[4:5], s[4:5], vcc
	s_nop 0
	v_writelane_b32 v254, s4, 62
	s_nop 1
	v_writelane_b32 v254, s5, 63
	v_cmp_lt_i32_e64 s[4:5], s28, v56
	v_or_b32_e32 v56, v64, v60
	v_sub_u32_e32 v57, v61, v56
	v_writelane_b32 v255, s4, 0
	v_cmp_gt_u32_e32 vcc, s18, v57
	v_or_b32_e32 v57, 1, v56
	v_writelane_b32 v255, s5, 1
	v_cmp_gt_i32_e64 s[4:5], s2, v56
	s_and_b64 s[4:5], s[4:5], vcc
	v_sub_u32_e32 v59, v61, v57
	v_writelane_b32 v255, s4, 2
	v_cmp_gt_u32_e32 vcc, s18, v59
	s_nop 0
	v_writelane_b32 v255, s5, 3
	v_cmp_lt_i32_e64 s[4:5], s28, v56
	s_nop 1
	v_writelane_b32 v255, s4, 4
	s_nop 1
	v_writelane_b32 v255, s5, 5
	v_cmp_gt_i32_e64 s[4:5], s2, v57
	s_and_b64 s[4:5], s[4:5], vcc
	v_or_b32_e32 v57, 2, v56
	v_writelane_b32 v255, s4, 6
	v_sub_u32_e32 v59, v61, v57
	v_cmp_gt_u32_e32 vcc, s18, v59
	v_writelane_b32 v255, s5, 7
	v_cmp_lt_i32_e64 s[4:5], s16, v56
	v_or_b32_e32 v56, 3, v56
	s_nop 0
	v_writelane_b32 v255, s4, 8
	s_nop 1
	v_writelane_b32 v255, s5, 9
	v_cmp_gt_i32_e64 s[4:5], s2, v57
	s_and_b64 s[4:5], s[4:5], vcc
	s_nop 0
	v_writelane_b32 v255, s4, 10
	s_nop 1
	v_writelane_b32 v255, s5, 11
	v_cmp_lt_i32_e64 s[4:5], s28, v57
	v_sub_u32_e32 v57, v61, v56
	v_cmp_gt_u32_e32 vcc, s18, v57
	v_writelane_b32 v255, s4, 12
	s_nop 1
	v_writelane_b32 v255, s5, 13
	v_cmp_gt_i32_e64 s[4:5], s2, v56
	s_and_b64 s[4:5], s[4:5], vcc
	s_nop 0
	v_writelane_b32 v255, s4, 14
	s_nop 1
	v_writelane_b32 v255, s5, 15
	v_cmp_lt_i32_e64 s[4:5], s28, v56
	v_or_b32_e32 v56, v66, v60
	v_sub_u32_e32 v57, v61, v56
	v_writelane_b32 v255, s4, 16
	v_cmp_gt_u32_e32 vcc, s18, v57
	v_or_b32_e32 v57, 1, v56
	v_writelane_b32 v255, s5, 17
	v_cmp_gt_i32_e64 s[4:5], s2, v56
	s_and_b64 s[40:41], s[4:5], vcc
	v_sub_u32_e32 v59, v61, v57
	v_cmp_gt_i32_e64 s[4:5], s2, v57
	v_or_b32_e32 v57, 2, v56
	v_cmp_gt_u32_e32 vcc, s18, v59
	v_sub_u32_e32 v59, v61, v57
	v_cmp_lt_i32_e64 s[74:75], s28, v56
	s_and_b64 s[52:53], s[4:5], vcc
	v_cmp_lt_i32_e64 s[76:77], s16, v56
	v_cmp_gt_u32_e32 vcc, s18, v59
	v_cmp_gt_i32_e64 s[4:5], s2, v57
	v_or_b32_e32 v56, 3, v56
	s_and_b64 s[20:21], s[4:5], vcc
	v_cmp_lt_i32_e64 s[78:79], s28, v57
	v_sub_u32_e32 v57, v61, v56
	v_cmp_gt_i32_e64 s[4:5], s2, v56
	v_cmp_lt_i32_e64 s[80:81], s28, v56
	v_or_b32_e32 v56, v68, v60
	v_cmp_gt_u32_e32 vcc, s18, v57
	v_sub_u32_e32 v57, v61, v56
	s_and_b64 s[54:55], s[4:5], vcc
	v_cmp_gt_u32_e32 vcc, s18, v57
	v_cmp_gt_i32_e64 s[4:5], s2, v56
	v_or_b32_e32 v57, 1, v56
	s_and_b64 s[42:43], s[4:5], vcc
	v_sub_u32_e32 v59, v61, v57
	v_cmp_gt_i32_e64 s[4:5], s2, v57
	v_or_b32_e32 v57, 2, v56
	v_cmp_gt_u32_e32 vcc, s18, v59
	v_sub_u32_e32 v59, v61, v57
	v_cmp_lt_i32_e64 s[82:83], s28, v56
	s_and_b64 s[56:57], s[4:5], vcc
	v_cmp_lt_i32_e64 s[84:85], s16, v56
	v_cmp_gt_u32_e32 vcc, s18, v59
	v_cmp_gt_i32_e64 s[4:5], s2, v57
	v_or_b32_e32 v56, 3, v56
	s_and_b64 s[22:23], s[4:5], vcc
	v_cmp_lt_i32_e64 s[86:87], s28, v57
	v_sub_u32_e32 v57, v61, v56
	v_cmp_gt_i32_e64 s[4:5], s2, v56
	v_cmp_lt_i32_e64 s[88:89], s28, v56
	v_or_b32_e32 v56, v70, v60
	v_cmp_gt_u32_e32 vcc, s18, v57
	v_sub_u32_e32 v57, v61, v56
	s_and_b64 s[58:59], s[4:5], vcc
	v_cmp_gt_u32_e32 vcc, s18, v57
	v_cmp_gt_i32_e64 s[4:5], s2, v56
	v_or_b32_e32 v57, 1, v56
	s_and_b64 s[44:45], s[4:5], vcc
	v_sub_u32_e32 v59, v61, v57
	v_cmp_gt_i32_e64 s[4:5], s2, v57
	v_or_b32_e32 v57, 2, v56
	v_cmp_gt_u32_e32 vcc, s18, v59
	v_sub_u32_e32 v59, v61, v57
	v_cmp_lt_i32_e64 s[90:91], s28, v56
	s_and_b64 s[60:61], s[4:5], vcc
	v_cmp_lt_i32_e64 s[92:93], s16, v56
	v_cmp_gt_u32_e32 vcc, s18, v59
	v_cmp_gt_i32_e64 s[4:5], s2, v57
	v_or_b32_e32 v56, 3, v56
	s_and_b64 s[24:25], s[4:5], vcc
	v_cmp_lt_i32_e64 s[94:95], s28, v57
	v_sub_u32_e32 v57, v61, v56
	v_cmp_gt_i32_e64 s[4:5], s2, v56
	v_cmp_lt_i32_e64 s[96:97], s28, v56
	v_or_b32_e32 v56, v72, v60
	v_cmp_gt_u32_e32 vcc, s18, v57
	v_sub_u32_e32 v57, v61, v56
	s_and_b64 s[62:63], s[4:5], vcc
	v_cmp_gt_u32_e32 vcc, s18, v57
	v_or_b32_e32 v57, 1, v56
	v_cmp_gt_i32_e64 s[4:5], s2, v56
	v_sub_u32_e32 v59, v61, v57
	v_cmp_gt_i32_e64 s[6:7], s2, v57
	v_or_b32_e32 v57, 2, v56
	s_and_b64 s[46:47], s[4:5], vcc
	v_cmp_gt_u32_e32 vcc, s18, v59
	v_sub_u32_e32 v59, v61, v57
	v_cmp_lt_i32_e64 s[4:5], s28, v56
	s_and_b64 s[64:65], s[6:7], vcc
	v_cmp_lt_i32_e64 s[6:7], s16, v56
	v_cmp_gt_u32_e32 vcc, s18, v59
	v_cmp_gt_i32_e64 s[8:9], s2, v57
	v_or_b32_e32 v56, 3, v56
	s_and_b64 s[26:27], s[8:9], vcc
	v_cmp_lt_i32_e64 s[8:9], s28, v57
	v_sub_u32_e32 v57, v61, v56
	v_cmp_gt_u32_e32 vcc, s18, v57
	v_cmp_gt_i32_e64 s[10:11], s2, v56
	s_and_b64 s[66:67], s[10:11], vcc
	v_cmp_lt_i32_e64 s[10:11], s28, v56
	v_or_b32_e32 v56, v74, v60
	v_sub_u32_e32 v57, v61, v56
	v_cmp_gt_u32_e32 vcc, s18, v57
	v_or_b32_e32 v57, 1, v56
	v_cmp_gt_i32_e64 s[12:13], s2, v56
	v_sub_u32_e32 v59, v61, v57
	v_cmp_gt_i32_e64 s[14:15], s2, v57
	v_or_b32_e32 v57, 2, v56
	s_and_b64 s[48:49], s[12:13], vcc
	v_cmp_gt_u32_e32 vcc, s18, v59
	v_sub_u32_e32 v59, v61, v57
	v_cmp_lt_i32_e64 s[12:13], s28, v56
	s_and_b64 s[68:69], s[14:15], vcc
	v_cmp_lt_i32_e64 s[14:15], s16, v56
	v_cmp_gt_u32_e32 vcc, s18, v59
	v_cmp_gt_i32_e64 s[16:17], s2, v57
	v_or_b32_e32 v56, 3, v56
	s_and_b64 s[38:39], s[16:17], vcc
	v_cmp_lt_i32_e64 s[16:17], s28, v57
	v_sub_u32_e32 v57, v61, v56
	v_cmp_gt_u32_e32 vcc, s18, v57
	v_cmp_gt_i32_e64 s[18:19], s2, v56
	s_and_b64 s[70:71], s[18:19], vcc
	v_cmp_lt_i32_e64 s[18:19], s28, v56
	v_add_u32_e32 v56, 0x9900, v35
	v_add3_u32 v108, v56, v37, v36
	v_lshlrev_b32_e32 v37, 5, v58
	v_add3_u32 v109, v56, v55, v36
	v_lshlrev_b32_e32 v55, 5, v63
	v_add3_u32 v111, v35, v37, v36
	v_add3_u32 v112, v56, v37, v36
	v_lshlrev_b32_e32 v37, 5, v65
	v_add3_u32 v110, v35, v55, v36
	v_add3_u32 v113, v56, v55, v36
	v_lshlrev_b32_e32 v55, 5, v67
	v_add3_u32 v115, v35, v37, v36
	v_add3_u32 v116, v56, v37, v36
	v_lshlrev_b32_e32 v37, 5, v69
	v_add3_u32 v114, v35, v55, v36
	v_add3_u32 v117, v56, v55, v36
	v_lshlrev_b32_e32 v55, 5, v71
	v_add3_u32 v119, v35, v37, v36
	v_add3_u32 v120, v56, v37, v36
	v_lshlrev_b32_e32 v37, 5, v73
	v_add3_u32 v118, v35, v55, v36
	v_add3_u32 v121, v56, v55, v36
	v_add3_u32 v122, v35, v37, v36
	v_add3_u32 v123, v56, v37, v36
	v_and_b32_e32 v131, 7, v201
	v_bfe_u32 v106, v201, 3, 3
	v_lshrrev_b32_e32 v107, 6, v201
	v_lshrrev_b32_e32 v108, 2, v131
	v_and_b32_e32 v109, 3, v131
	v_lshlrev_b32_e32 v110, 5, v106
	v_lshl_add_u32 v110, v109, 3, v110
	v_lshl_add_u32 v110, v108, 6, v110
	v_and_b32_e32 v110, 0xff, v110
	v_lshl_add_u32 v110, v108, 9, v110
	v_lshl_add_u32 v128, v107, 10, v110
	v_and_b32_e32 v111, 63, v201
	v_and_b32_e32 v112, 15, v111
	v_lshrrev_b32_e32 v113, 4, v111
	v_and_b32_e32 v114, 1, v113
	v_lshrrev_b32_e32 v115, 1, v113
	v_lshrrev_b32_e32 v116, 2, v112
	v_and_b32_e32 v117, 3, v112
	v_lshl_add_u32 v116, v114, 2, v116
	v_lshlrev_b32_e32 v116, 5, v116
	v_lshl_add_u32 v116, v117, 3, v116
	v_lshlrev_b32_e32 v118, 11, v107
	v_lshl_add_u32 v118, v115, 10, v118
	v_add_u32_e32 v129, v118, v116
	v_add_u32_e32 v116, 64, v116
	v_and_b32_e32 v116, 0xff, v116
	v_add_u32_e32 v130, v118, v116
	v_add_u32_e32 v130, 0x200, v130
	s_waitcnt vmcnt(0)
	v_mov_b64_e32 v[34:35], v[46:47]
	v_mov_b64_e32 v[36:37], v[48:49]
	v_readfirstlane_b32 s98, v201
	s_cmp_lt_u32 s98, 0x100
	s_cbranch_scc1 .Lattn_prio_skip
	s_setprio 1
.Lattn_prio_skip:
	s_branch .LBB0_488
	s_nop 0
	s_nop 0
	s_nop 0
	s_nop 0
	s_nop 0
	s_nop 0
	s_nop 0
	s_nop 0
	s_nop 0
	s_nop 0
	s_nop 0
	s_nop 0

.LBB0_508:
	s_setprio 0
	s_mov_b64 s[4:5], 0
